# attention phase: static s_setprio 1 for waves 0-3 (one wave of each SIMD pair), reset at phase end
# baseline (speedup 1.0000x reference)
.LBB0_689:
	s_cmp_lt_i32 s30, 6
	s_cselect_b64 s[4:5], -1, 0
	s_cmp_gt_i32 s31, 5
	s_cselect_b64 s[6:7], -1, 0
	s_and_b64 s[4:5], s[4:5], s[6:7]
	s_andn2_b64 vcc, exec, s[4:5]
	s_cbranch_vccnz .LBB0_766
	s_mov_b64 s[6:7], s[0:1]
	v_mov_b32_e32 v1, v0
	s_cmpk_gt_i32 s48, 0x3ff
	s_cbranch_scc1 .LBB0_712
	v_readfirstlane_b32 s8, v0
	s_load_dwordx2 s[50:51], s[6:7], 0xe0
	s_lshr_b32 s8, s8, 6
	s_cmp_lt_u32 s8, 4
	s_cbranch_scc0 .Latt_prio_done
	s_setprio 1
.Latt_prio_done:
	s_mov_b32 s12, 0
	s_mov_b32 s39, 0x20000
	s_movk_i32 s3, 0xc0
	s_mov_b32 s38, 0x18c000
	s_waitcnt lgkmcnt(0)
	s_add_u32 s4, s50, 0x17200000
	s_addc_u32 s5, s51, 0
	s_add_u32 s35, s50, 0x1d200000
	s_addc_u32 s46, s51, 0
	s_add_u32 s47, s50, 0x23500000
	s_mov_b32 s10, 0x108000
	s_addc_u32 s49, s51, 0
	v_mov_b32_e32 v155, 0
	s_mov_b32 s42, 0x108000
	s_mov_b32 s43, s39
	s_movk_i32 s53, 0x2000
	s_mov_b32 s60, 0x2aaaaaab
	v_mov_b32_e32 v1, 0x7f7f7f7f
	s_mov_b32 s61, 0x422646e2
	s_mov_b32 s52, 0x3dd53b94
	v_mov_b32_e32 v176, 0xf149f2ca
	s_mov_b32 s62, 0xbdd53b94
	s_movk_i32 s63, 0x3000
	s_movk_i32 s64, 0x6000
	s_movk_i32 s65, 0x4000
	s_mov_b32 s13, s12
	s_mov_b32 s14, s12
	s_mov_b32 s15, s12
	s_mov_b32 s16, s12
	s_mov_b32 s17, s12
	s_mov_b32 s18, s12
	s_mov_b32 s19, s12
	s_mov_b32 s20, s12
	s_mov_b32 s21, s12
	s_mov_b32 s22, s12
	s_mov_b32 s23, s12
	s_mov_b32 s24, s12
	s_mov_b32 s25, s12
	s_mov_b32 s26, s12
	s_mov_b32 s27, s12
	s_movk_i32 s66, 0x1800
	s_movk_i32 s67, 0x2200
	s_movk_i32 s68, 0x7fff
	s_movk_i32 s69, 0x110
	s_mov_b32 s70, 0xc0f00000
	v_mov_b32_e32 v177, 0x40f00000
	s_mov_b32 s71, s48
	s_branch .LBB0_693

.LBB0_712:
	s_setprio 0
	s_cmp_gt_i32 s31, 6
	s_cbranch_scc0 .LBB0_766
	s_waitcnt vmcnt(0)
	s_waitcnt vmcnt(0) lgkmcnt(0)
	s_barrier
	s_and_saveexec_b64 s[6:7], s[92:93]
	s_cbranch_execz .LBB0_765
	s_add_i32 s3, 0, 0x27020
	v_mov_b32_e32 v1, s3
	s_waitcnt vmcnt(0) expcnt(0) lgkmcnt(0)
	ds_read_b32 v3, v1
	s_add_i32 s3, 0, 0x27024
	v_mov_b32_e32 v1, s3
	ds_read_b32 v1, v1
	s_waitcnt lgkmcnt(1)
	v_cmp_ne_u32_e32 vcc, 0, v3
	s_cbranch_vccnz .LBB0_729
	s_add_u32 s8, s28, 0x4200
	s_addc_u32 s9, s29, 0
	s_add_u32 s10, s28, 0x4400
	s_addc_u32 s11, s29, 0
	s_add_u32 s12, s28, 0x4500
	s_addc_u32 s13, s29, 0
	s_add_u32 s14, s28, 0x4600
	s_addc_u32 s15, s29, 0
	s_add_u32 s16, s28, 0x4700
	s_addc_u32 s17, s29, 0
	s_add_u32 s18, s28, 0x4800
	s_addc_u32 s19, s29, 0
	s_add_u32 s20, s28, 0x4900
	s_addc_u32 s21, s29, 0
	s_add_u32 s22, s28, 0x4a00
	s_addc_u32 s23, s29, 0
	s_add_u32 s24, s28, 0x4b00
	s_addc_u32 s25, s29, 0
	s_add_u32 s26, s28, 0x4c00
	s_addc_u32 s27, s29, 0
	s_add_u32 s36, s28, 0x4d00
	s_addc_u32 s37, s29, 0
	s_add_u32 s38, s28, 0x4e00
	s_addc_u32 s39, s29, 0
	s_add_u32 s40, s28, 0x4f00
	s_addc_u32 s41, s29, 0
	s_add_u32 s42, s28, 0x5000
	s_load_dwordx2 s[4:5], s[90:91], 0x4
	s_addc_u32 s43, s29, 0
	s_add_u32 s50, s28, 0x5100
	s_addc_u32 s51, s29, 0
	s_add_u32 s52, s28, 0x5200
	s_addc_u32 s53, s29, 0
	s_waitcnt lgkmcnt(0)
	s_mul_i32 s3, s4, s34
	s_add_u32 s54, s28, 0x5300
	s_mul_i32 s3, s3, s5
	s_addc_u32 s55, s29, 0
	s_mov_b32 s4, 1
	v_mov_b32_e32 v17, 0
	s_branch .LBB0_717
